# phase-0 weight conversion: rotate workgroup numbering per convT call to spread surplus tiles
# baseline (speedup 1.0000x reference)
.LBB0_6:
	v_readlane_b32 s20, v252, 0
	v_readlane_b32 s21, v252, 1
	s_add_u32 s0, s20, 0x208
	s_load_dwordx16 s[56:71], s[20:21], 0x130
	s_addc_u32 s1, s21, 0
	v_writelane_b32 v252, s0, 10
	s_load_dwordx16 s[36:51], s[20:21], 0x170
	v_lshrrev_b32_e32 v1, 20, v0
	v_writelane_b32 v252, s1, 11
	s_add_u32 s0, s20, 0x200
	s_addc_u32 s1, s21, 0
	v_writelane_b32 v252, s0, 12
	s_waitcnt lgkmcnt(0)
	s_cmp_lg_u64 s[70:71], 0
	s_cselect_b64 s[4:5], -1, 0
	v_writelane_b32 v252, s1, 13
	v_writelane_b32 v252, s4, 14
	s_load_dword s1, s[20:21], 0x2a0
	s_mul_i32 s0, s35, s34
	v_writelane_b32 v252, s5, 15
	s_add_u32 s4, s36, 0x3000000
	s_addc_u32 s5, s37, 0
	v_writelane_b32 v252, s4, 16
	s_waitcnt lgkmcnt(0)
	s_mul_i32 s90, s0, s1
	v_lshrrev_b32_e32 v0, 10, v0
	v_writelane_b32 v252, s5, 17
	s_add_u32 s4, s36, 0x2000000
	s_addc_u32 s5, s37, 0
	v_writelane_b32 v252, s4, 18
	v_or_b32_e32 v0, v0, v1
	v_mov_b32_e32 v1, 0
	v_writelane_b32 v252, s5, 19
	v_mbcnt_lo_u32_b32 v2, -1, 0
	v_readlane_b32 s4, v252, 6
	v_readlane_b32 s5, v252, 7
	s_add_u32 s0, s4, 0x200
	s_addc_u32 s1, s5, 0
	v_writelane_b32 v252, s0, 20
	v_mov_b32_e32 v197, 0x358637bd
	v_mov_b32_e32 v200, 0x3000
	v_writelane_b32 v252, s1, 21
	s_add_u32 s0, s4, 0x1000
	s_addc_u32 s1, s5, 0
	v_writelane_b32 v252, s0, 22
	v_mov_b32_e32 v201, 0x6000
	v_mov_b32_e32 v202, 0x3a27c5ac
	v_writelane_b32 v252, s1, 23
	s_add_u32 s0, s4, 0x1100
	s_addc_u32 s1, s5, 0
	v_writelane_b32 v252, s0, 24
	v_mov_b32_e32 v204, 0x260
	v_mov_b32_e32 v206, 0x3c0881c4
	v_writelane_b32 v252, s1, 25
	s_add_u32 s0, s4, 0x1200
	s_addc_u32 s1, s5, 0
	v_writelane_b32 v252, s0, 26
	v_mov_b32_e32 v207, 0xbab64f3b
	v_mbcnt_hi_u32_b32 v209, -1, v2
	v_writelane_b32 v252, s1, 27
	s_add_u32 s0, s4, 0x1300
	s_addc_u32 s1, s5, 0
	v_writelane_b32 v252, s0, 28
	s_cmp_eq_u32 s3, 15
	v_mov_b32_e32 v210, v1
	v_writelane_b32 v252, s1, 29
	s_cselect_b64 s[0:1], -1, 0
	v_writelane_b32 v252, s0, 30
	s_cmp_eq_u32 s3, 14
	v_mov_b32_e32 v211, v1
	v_writelane_b32 v252, s1, 31
	s_cselect_b64 s[0:1], -1, 0
	v_writelane_b32 v252, s0, 32
	s_cmp_eq_u32 s3, 13
	v_mov_b32_e32 v212, v1
	v_writelane_b32 v252, s1, 33
	s_cselect_b64 s[0:1], -1, 0
	v_writelane_b32 v252, s0, 34
	s_cmp_eq_u32 s3, 12
	v_mov_b32_e32 v213, v1
	v_writelane_b32 v252, s1, 35
	s_cselect_b64 s[0:1], -1, 0
	v_writelane_b32 v252, s0, 36
	s_cmp_eq_u32 s3, 11
	v_mov_b32_e32 v208, 0xfffffd80
	v_writelane_b32 v252, s1, 37
	s_cselect_b64 s[0:1], -1, 0
	v_writelane_b32 v252, s0, 38
	s_cmp_eq_u32 s3, 10
	v_mov_b32_e32 v203, 0xfffffce0
	v_writelane_b32 v252, s1, 39
	s_cselect_b64 s[0:1], -1, 0
	v_writelane_b32 v252, s0, 40
	s_cmp_eq_u32 s3, 9
	v_mov_b32_e32 v223, 0xfffffc40
	v_writelane_b32 v252, s1, 41
	s_cselect_b64 s[0:1], -1, 0
	v_writelane_b32 v252, s0, 42
	s_cmp_eq_u32 s3, 8
	v_mov_b32_e32 v229, 0xfffffb50
	v_writelane_b32 v252, s1, 43
	s_cselect_b64 s[0:1], -1, 0
	v_writelane_b32 v252, s0, 44
	s_cmp_eq_u32 s3, 7
	v_mov_b32_e32 v230, 0xfffffb00
	v_writelane_b32 v252, s1, 45
	s_cselect_b64 s[0:1], -1, 0
	v_writelane_b32 v252, s0, 46
	s_cmp_eq_u32 s3, 6
	v_mov_b32_e32 v205, 0xfffff9c0
	v_writelane_b32 v252, s1, 47
	s_cselect_b64 s[0:1], -1, 0
	v_writelane_b32 v252, s0, 48
	s_cmp_eq_u32 s3, 5
	v_mov_b32_e32 v198, 0x7f800000
	v_writelane_b32 v252, s1, 49
	s_cselect_b64 s[0:1], -1, 0
	v_writelane_b32 v252, s0, 50
	s_cmp_eq_u32 s3, 4
	v_mov_b32_e32 v199, 0x100
	v_writelane_b32 v252, s1, 51
	s_cselect_b64 s[0:1], -1, 0
	v_writelane_b32 v252, s0, 52
	s_cmp_eq_u32 s3, 3
	v_mov_b32_e32 v250, 0x41b17218
	v_writelane_b32 v252, s1, 53
	s_cselect_b64 s[0:1], -1, 0
	v_writelane_b32 v252, s0, 54
	s_cmp_eq_u32 s3, 2
	v_mov_b32_e32 v251, 0x1c00
	v_writelane_b32 v252, s1, 55
	s_cselect_b64 s[0:1], -1, 0
	v_writelane_b32 v252, s0, 56
	s_cmp_eq_u32 s3, 1
	v_mov_b32_e32 v222, 0x800
	v_writelane_b32 v252, s1, 57
	s_cselect_b64 s[0:1], -1, 0
	v_writelane_b32 v252, s0, 58
	s_cmp_eq_u32 s3, 0
	v_not_b32_e32 v224, 63
	v_writelane_b32 v252, s1, 59
	s_cselect_b64 s[0:1], -1, 0
	v_writelane_b32 v252, s0, 60
	v_not_b32_e32 v225, 31
	v_mov_b32_e32 v226, 0xffc00000
	v_writelane_b32 v252, s1, 61
	s_lshl_b32 s0, s3, 8
	s_add_u32 s0, s4, s0
	s_addc_u32 s1, s5, 0
	s_add_u32 s6, s0, 0x1400
	s_addc_u32 s7, s1, 0
	s_add_u32 s0, s0, 0x2400
	s_addc_u32 s1, s1, 0
	v_writelane_b32 v253, s0, 0
	v_writelane_b32 v252, s6, 62
	v_mov_b32_e32 v227, 0x7fc00000
	v_writelane_b32 v253, s1, 1
	s_add_u32 s0, s4, 0x3400
	s_addc_u32 s1, s5, 0
	v_writelane_b32 v253, s0, 2
	v_writelane_b32 v252, s7, 63
	v_mov_b32_e32 v228, 0x900
	v_writelane_b32 v253, s1, 3
	s_add_u32 s0, s4, 0x3500
	s_addc_u32 s1, s5, 0
	v_writelane_b32 v253, s0, 4
	s_mov_b32 s3, 0x2aaaaaab
	s_mov_b32 s96, 0x3c000
	v_writelane_b32 v253, s1, 5
	s_movk_i32 s0, 0x3ff
	v_and_or_b32 v0, v0, s0, v196
	s_load_dwordx2 s[0:1], s[20:21], 0x288
	s_load_dwordx4 s[4:7], s[20:21], 0x278
	s_movk_i32 s93, 0x1f8
	s_mov_b32 s35, 0x18000
	s_mov_b32 s97, 0x54000
	s_mov_b32 s31, 0
	s_waitcnt lgkmcnt(0)
	s_add_u32 s8, s6, 0x80000
	v_writelane_b32 v253, s4, 6
	s_addc_u32 s9, s7, 0
	s_nop 0
	v_writelane_b32 v253, s5, 7
	v_writelane_b32 v253, s6, 8
	v_writelane_b32 v253, s7, 9
	v_writelane_b32 v253, s8, 10
	s_add_u32 s4, s62, 0x100000
	s_addc_u32 s5, s63, 0
	v_writelane_b32 v253, s9, 11
	v_writelane_b32 v253, s4, 12
	s_nop 1
	v_writelane_b32 v253, s5, 13
	s_add_u32 s4, s42, 8
	v_writelane_b32 v253, s36, 14
	s_addc_u32 s5, s43, 0
	s_nop 0
	v_writelane_b32 v253, s37, 15
	v_writelane_b32 v253, s38, 16
	v_writelane_b32 v253, s39, 17
	v_writelane_b32 v253, s40, 18
	v_writelane_b32 v253, s41, 19
	v_writelane_b32 v253, s42, 20
	v_writelane_b32 v253, s43, 21
	v_writelane_b32 v253, s44, 22
	v_writelane_b32 v253, s45, 23
	v_writelane_b32 v253, s46, 24
	v_writelane_b32 v253, s47, 25
	v_writelane_b32 v253, s48, 26
	v_writelane_b32 v253, s49, 27
	v_writelane_b32 v253, s50, 28
	v_writelane_b32 v253, s51, 29
	v_writelane_b32 v253, s4, 30
	s_mov_b32 s36, 0xc000
	s_mov_b32 s39, 0x3e8293ee
	v_writelane_b32 v253, s5, 31
	s_add_u32 s4, s0, 0x2400
	v_writelane_b32 v253, s0, 32
	s_addc_u32 s5, s1, 0
	s_mov_b32 s38, 0x42000
	v_writelane_b32 v253, s1, 33
	v_writelane_b32 v253, s4, 34
	s_mov_b32 s37, 0x4ec4ec4f
	s_nop 0
	v_writelane_b32 v253, s5, 35
	s_load_dwordx8 s[4:11], s[20:21], 0x230
	s_waitcnt lgkmcnt(0)
	s_add_u32 s0, s4, 0x800
	v_writelane_b32 v253, s4, 36
	s_addc_u32 s1, s5, 0
	s_nop 0
	v_writelane_b32 v253, s5, 37
	v_writelane_b32 v253, s6, 38
	v_writelane_b32 v253, s7, 39
	v_writelane_b32 v253, s8, 40
	v_writelane_b32 v253, s9, 41
	v_writelane_b32 v253, s10, 42
	v_writelane_b32 v253, s11, 43
	s_load_dwordx16 s[4:19], s[20:21], 0x1f0
	v_writelane_b32 v253, s0, 44
	s_nop 1
	v_writelane_b32 v253, s1, 45
	s_waitcnt lgkmcnt(0)
	s_add_u32 s0, s16, 0x1000
	v_writelane_b32 v253, s4, 46
	s_addc_u32 s1, s17, 0
	s_nop 0
	v_writelane_b32 v253, s5, 47
	v_writelane_b32 v253, s6, 48
	v_writelane_b32 v253, s7, 49
	v_writelane_b32 v253, s8, 50
	v_writelane_b32 v253, s9, 51
	v_writelane_b32 v253, s10, 52
	v_writelane_b32 v253, s11, 53
	v_writelane_b32 v253, s12, 54
	v_writelane_b32 v253, s13, 55
	v_writelane_b32 v253, s14, 56
	v_writelane_b32 v253, s15, 57
	v_writelane_b32 v253, s16, 58
	v_writelane_b32 v253, s17, 59
	v_writelane_b32 v253, s18, 60
	v_writelane_b32 v253, s19, 61
	s_load_dwordx16 s[4:19], s[20:21], 0x1b0
	v_writelane_b32 v253, s0, 62
	s_nop 1
	v_writelane_b32 v253, s1, 63
	s_waitcnt lgkmcnt(0)
	s_add_u32 s0, s14, 0x200
	v_writelane_b32 v254, s4, 0
	s_addc_u32 s1, s15, 0
	s_nop 0
	v_writelane_b32 v254, s5, 1
	v_writelane_b32 v254, s6, 2
	v_writelane_b32 v254, s7, 3
	v_writelane_b32 v254, s8, 4
	v_writelane_b32 v254, s9, 5
	v_writelane_b32 v254, s10, 6
	v_writelane_b32 v254, s11, 7
	v_writelane_b32 v254, s12, 8
	v_writelane_b32 v254, s13, 9
	v_writelane_b32 v254, s14, 10
	v_writelane_b32 v254, s15, 11
	v_writelane_b32 v254, s16, 12
	v_writelane_b32 v254, s17, 13
	v_writelane_b32 v254, s18, 14
	v_writelane_b32 v254, s19, 15
	v_writelane_b32 v254, s0, 16
	s_load_dwordx4 s[4:7], s[20:21], 0x250
	s_nop 0
	v_writelane_b32 v254, s1, 17
	s_add_i32 s0, 16, 0x14000
	v_writelane_b32 v254, s0, 18
	v_readlane_b32 s0, v252, 8
	v_readlane_b32 s1, v252, 9
	s_mov_b32 s30, s0
	v_cmp_eq_u32_e64 s[0:1], 0, v0
	s_nop 1
	v_writelane_b32 v254, s0, 19
	s_nop 1
	v_writelane_b32 v254, s1, 20
	s_load_dwordx2 s[0:1], s[20:21], 0x260
	s_load_dwordx8 s[8:15], s[20:21], 0x0
	s_load_dwordx16 s[40:55], s[20:21], 0x30
	s_load_dwordx16 s[72:87], s[20:21], 0xf0
	s_waitcnt lgkmcnt(0)
	v_writelane_b32 v254, s0, 21
	s_nop 1
	v_writelane_b32 v254, s1, 22
	v_writelane_b32 v254, s4, 23
	s_nop 1
	v_writelane_b32 v254, s5, 24
	v_writelane_b32 v254, s6, 25
	v_writelane_b32 v254, s7, 26
	v_writelane_b32 v254, s40, 27
	s_nop 1
	v_writelane_b32 v254, s41, 28
	v_writelane_b32 v254, s42, 29
	v_writelane_b32 v254, s43, 30
	v_writelane_b32 v254, s44, 31
	v_writelane_b32 v254, s45, 32
	v_writelane_b32 v254, s46, 33
	v_writelane_b32 v254, s47, 34
	v_writelane_b32 v254, s48, 35
	v_writelane_b32 v254, s49, 36
	v_writelane_b32 v254, s50, 37
	v_writelane_b32 v254, s51, 38
	v_writelane_b32 v254, s52, 39
	v_writelane_b32 v254, s53, 40
	v_writelane_b32 v254, s54, 41
	v_writelane_b32 v254, s55, 42
	s_load_dwordx16 s[40:55], s[20:21], 0xb0
	s_waitcnt lgkmcnt(0)
	v_writelane_b32 v254, s40, 43
	s_nop 1
	v_writelane_b32 v254, s41, 44
	v_writelane_b32 v254, s42, 45
	v_writelane_b32 v254, s43, 46
	v_writelane_b32 v254, s44, 47
	v_writelane_b32 v254, s45, 48
	v_writelane_b32 v254, s46, 49
	v_writelane_b32 v254, s47, 50
	v_writelane_b32 v254, s48, 51
	v_writelane_b32 v254, s49, 52
	v_writelane_b32 v254, s50, 53
	v_writelane_b32 v254, s51, 54
	v_writelane_b32 v254, s52, 55
	v_writelane_b32 v254, s53, 56
	v_writelane_b32 v254, s54, 57
	v_writelane_b32 v254, s55, 58
	s_load_dwordx16 s[40:55], s[20:21], 0x70
	s_waitcnt lgkmcnt(0)
	v_writelane_b32 v254, s40, 59
	s_nop 1
	v_writelane_b32 v255, s45, 0
	v_writelane_b32 v255, s46, 1
	v_writelane_b32 v255, s47, 2
	v_writelane_b32 v255, s48, 3
	v_writelane_b32 v255, s49, 4
	v_writelane_b32 v255, s50, 5
	v_writelane_b32 v255, s51, 6
	v_writelane_b32 v255, s52, 7
	v_writelane_b32 v255, s53, 8
	v_writelane_b32 v255, s54, 9
	v_writelane_b32 v255, s55, 10
	v_writelane_b32 v255, s90, 11
	v_writelane_b32 v255, s8, 12
	v_writelane_b32 v254, s41, 60
	v_writelane_b32 v254, s42, 61
	v_writelane_b32 v255, s9, 13
	v_writelane_b32 v255, s10, 14
	v_writelane_b32 v255, s11, 15
	v_writelane_b32 v255, s12, 16
	v_writelane_b32 v255, s13, 17
	v_writelane_b32 v254, s43, 62
	v_writelane_b32 v255, s14, 18
	v_writelane_b32 v254, s44, 63
	v_writelane_b32 v255, s15, 19
	v_writelane_b32 v255, 0, 44
	s_branch .LBB0_11

.LBB0_1026:
	v_mov_b32_e32 v4, v196
	v_readlane_b32 vcc_hi, v255, 44
	s_sub_i32 s0, s2, vcc_hi
	s_cmp_lt_i32 s0, 0
	s_cselect_b32 vcc_lo, s34, 0
	s_add_i32 s0, s0, vcc_lo
	s_add_i32 vcc_hi, vcc_hi, 160
	s_cmp_ge_u32 vcc_hi, s34
	s_cselect_b32 vcc_lo, s34, 0
	s_sub_i32 vcc_hi, vcc_hi, vcc_lo
	s_nop 0
	v_writelane_b32 v255, vcc_hi, 44
	v_mov_b32_e32 v0, v196
	s_lshl_b32 s0, s0, 1
	v_readfirstlane_b32 s1, v0
	s_ashr_i32 s1, s1, 8
	v_mov_b32_e32 v0, v196
	s_add_i32 s1, s1, s0
	s_nop 0
	v_readfirstlane_b32 s0, v0
	s_ashr_i32 s0, s0, 8
	s_sub_i32 s22, s1, s0
	s_cmpk_gt_i32 s22, 0x33f
	s_cbranch_scc1 .LBB0_1031
	v_readlane_b32 s4, v253, 14
	s_mul_i32 s0, s40, 0x680000
	v_readlane_b32 s6, v253, 16
	v_readlane_b32 s5, v253, 15
	v_readlane_b32 s7, v253, 17
	v_readlane_b32 s8, v253, 18
	v_readlane_b32 s9, v253, 19
	v_readlane_b32 s10, v253, 20
	v_readlane_b32 s11, v253, 21
	v_readlane_b32 s12, v253, 22
	v_readlane_b32 s13, v253, 23
	v_readlane_b32 s14, v253, 24
	v_readlane_b32 s15, v253, 25
	v_readlane_b32 s16, v253, 26
	v_readlane_b32 s17, v253, 27
	v_readlane_b32 s18, v253, 28
	v_readlane_b32 s19, v253, 29
	s_add_u32 s0, s6, s0
	s_addc_u32 s1, s7, 0
	v_readlane_b32 s4, v254, 59
	s_mul_i32 s20, s40, 0xd00000
	v_readlane_b32 s8, v254, 63
	v_mov_b32_e32 v0, v196
	v_readlane_b32 s9, v255, 0
	s_add_u32 s20, s8, s20
	s_addc_u32 s21, s9, 0
	v_readfirstlane_b32 s23, v0
	s_ashr_i32 s23, s23, 8
	s_add_i32 s23, s23, s22
	s_min_i32 s23, s23, 0x33f
	s_ashr_i32 s26, s23, 31
	s_lshr_b32 s26, s26, 28
	s_add_i32 s26, s23, s26
	s_and_b32 s27, s26, 0x3fff0
	v_bfe_u32 v6, v4, 6, 2
	s_sub_i32 s23, s23, s27
	v_lshl_or_b32 v5, s23, 6, v6
	s_lshl_b32 s23, s26, 2
	s_and_b32 s26, s23, 0xffffffc0
	s_ashr_i32 s27, s26, 31
	s_lshl_b64 s[26:27], s[26:27], 2
	s_add_u32 s26, s20, s26
	v_lshlrev_b32_e32 v0, 2, v4
	s_addc_u32 s27, s21, s27
	v_and_b32_e32 v0, 0xfc, v0
	s_waitcnt vmcnt(1)
	v_mul_lo_u32 v8, v5, s50
	v_lshl_add_u64 v[2:3], s[26:27], 0, v[0:1]
	v_ashrrev_i32_e32 v9, 31, v8
	v_lshl_add_u64 v[2:3], v[8:9], 2, v[2:3]
	v_add_co_u32_e32 v8, vcc, s48, v2
	s_mov_b32 s4, 0x27000
	s_nop 0
	v_addc_co_u32_e32 v9, vcc, 0, v3, vcc
	v_add_co_u32_e32 v10, vcc, s55, v2
	s_mov_b32 s23, 0xa9000
	s_nop 0
	v_addc_co_u32_e32 v11, vcc, 0, v3, vcc
	v_add_co_u32_e32 v12, vcc, s4, v2
	s_mov_b32 s4, 0x34000
	s_nop 0
	v_addc_co_u32_e32 v13, vcc, 0, v3, vcc
	v_add_co_u32_e32 v14, vcc, s4, v2
	s_mov_b32 s4, 0x41000
	s_nop 0
	v_addc_co_u32_e32 v15, vcc, 0, v3, vcc
	s_waitcnt vmcnt(0)
	v_add_co_u32_e32 v16, vcc, s4, v2
	s_mov_b32 s4, 0x5b000
	s_nop 0
	v_addc_co_u32_e32 v17, vcc, 0, v3, vcc
	v_add_co_u32_e32 v20, vcc, s53, v2
	v_mov_b32_e32 v5, v1
	s_nop 0
	v_addc_co_u32_e32 v21, vcc, 0, v3, vcc
	v_add_co_u32_e32 v22, vcc, s4, v2
	s_mov_b32 s4, 0x68000
	s_waitcnt lgkmcnt(4)
	v_addc_co_u32_e32 v23, vcc, 0, v3, vcc
	global_load_dword v7, v[2:3], off nt
	s_nop 0
	global_load_dword v9, v[8:9], off nt
	s_nop 0
	global_load_dword v10, v[10:11], off nt
	s_nop 0
	global_load_dword v11, v[12:13], off nt
	s_nop 0
	global_load_dword v12, v[14:15], off nt
	s_nop 0
	global_load_dword v14, v[16:17], off nt
	s_nop 0
	global_load_dword v16, v[20:21], off nt
	global_load_dword v17, v[22:23], off nt
	v_add_co_u32_e32 v20, vcc, s4, v2
	s_mov_b32 s4, 0x75000
	s_nop 0
	v_addc_co_u32_e32 v21, vcc, 0, v3, vcc
	v_add_co_u32_e32 v22, vcc, s4, v2
	s_mov_b32 s4, 0x82000
	s_nop 0
	v_addc_co_u32_e32 v23, vcc, 0, v3, vcc
	v_add_co_u32_e32 v24, vcc, s4, v2
	s_mov_b32 s4, 0x8f000
	s_nop 0
	v_addc_co_u32_e32 v25, vcc, 0, v3, vcc
	v_add_co_u32_e32 v26, vcc, s4, v2
	s_mov_b32 s4, 0x9c000
	s_nop 0
	v_addc_co_u32_e32 v27, vcc, 0, v3, vcc
	v_add_co_u32_e32 v28, vcc, s4, v2
	v_bfe_u32 v8, v4, 3, 5
	s_nop 0
	v_addc_co_u32_e32 v29, vcc, 0, v3, vcc
	v_add_co_u32_e32 v30, vcc, s23, v2
	s_mov_b32 s23, 0xb6000
	s_nop 0
	v_addc_co_u32_e32 v31, vcc, 0, v3, vcc
	s_waitcnt lgkmcnt(0)
	v_add_co_u32_e32 v32, vcc, s23, v2
	s_mov_b32 s23, 0xc3000
	s_nop 0
	v_addc_co_u32_e32 v33, vcc, 0, v3, vcc
	v_add_co_u32_e32 v2, vcc, s23, v2
	v_lshlrev_b32_e32 v4, 3, v4
	s_nop 0
	v_addc_co_u32_e32 v3, vcc, 0, v3, vcc
	global_load_dword v19, v[20:21], off nt
	s_nop 0
	global_load_dword v20, v[22:23], off nt
	global_load_dword v21, v[24:25], off nt
	s_nop 0
	global_load_dword v22, v[26:27], off nt
	global_load_dword v23, v[28:29], off nt
	global_load_dword v24, v[30:31], off nt
	global_load_dword v25, v[32:33], off nt
	s_nop 0
	global_load_dword v26, v[2:3], off nt
	v_and_b32_e32 v13, 56, v4
	v_mul_u32_u24_e32 v15, 0x41, v13
	v_lshlrev_b32_e32 v15, 2, v15
	v_lshlrev_b32_e32 v27, 2, v8
	v_lshlrev_b32_e32 v4, 1, v13
	v_add3_u32 v15, s33, v15, v27
	v_mul_u32_u24_e32 v27, 0x104, v6
	v_lshl_add_u64 v[2:3], s[20:21], 0, v[0:1]
	v_lshl_add_u64 v[4:5], s[0:1], 0, v[4:5]
	v_or_b32_e32 v13, 32, v8
	v_add3_u32 v0, s33, v27, v0
	v_readlane_b32 s5, v254, 60
	v_readlane_b32 s6, v254, 61
	v_readlane_b32 s7, v254, 62
	v_readlane_b32 s10, v255, 1
	v_readlane_b32 s11, v255, 2
	v_readlane_b32 s12, v255, 3
	v_readlane_b32 s13, v255, 4
	v_readlane_b32 s14, v255, 5
	v_readlane_b32 s15, v255, 6
	v_readlane_b32 s16, v255, 7
	v_readlane_b32 s17, v255, 8
	v_readlane_b32 s18, v255, 9
	v_readlane_b32 s19, v255, 10
	s_branch .LBB0_1029

.LBB0_1031:
	v_mov_b32_e32 v4, v196
	v_readlane_b32 vcc_hi, v255, 44
	s_sub_i32 s0, s2, vcc_hi
	s_cmp_lt_i32 s0, 0
	s_cselect_b32 vcc_lo, s34, 0
	s_add_i32 s0, s0, vcc_lo
	s_add_i32 vcc_hi, vcc_hi, 128
	s_cmp_ge_u32 vcc_hi, s34
	s_cselect_b32 vcc_lo, s34, 0
	s_sub_i32 vcc_hi, vcc_hi, vcc_lo
	s_nop 0
	v_writelane_b32 v255, vcc_hi, 44
	v_mov_b32_e32 v0, v196
	s_lshl_b32 s0, s0, 1
	v_readfirstlane_b32 s1, v0
	s_ashr_i32 s1, s1, 8
	v_mov_b32_e32 v0, v196
	s_add_i32 s1, s1, s0
	s_lshl_b64 s[42:43], s[40:41], 20
	v_readfirstlane_b32 s0, v0
	s_ashr_i32 s0, s0, 8
	s_sub_i32 s22, s1, s0
	s_cmpk_gt_i32 s22, 0xff
	s_cbranch_scc1 .LBB0_1036
	v_readlane_b32 s4, v253, 14
	s_lshl_b64 s[0:1], s[42:43], 1
	v_readlane_b32 s8, v253, 18
	v_readlane_b32 s5, v253, 15
	v_readlane_b32 s6, v253, 16
	v_readlane_b32 s7, v253, 17
	v_readlane_b32 s9, v253, 19
	v_readlane_b32 s10, v253, 20
	v_readlane_b32 s11, v253, 21
	v_readlane_b32 s12, v253, 22
	v_readlane_b32 s13, v253, 23
	v_readlane_b32 s14, v253, 24
	v_readlane_b32 s15, v253, 25
	v_readlane_b32 s16, v253, 26
	v_readlane_b32 s17, v253, 27
	v_readlane_b32 s18, v253, 28
	v_readlane_b32 s19, v253, 29
	s_add_u32 s0, s8, s0
	s_addc_u32 s1, s9, s1
	v_readlane_b32 s4, v254, 59
	s_lshl_b64 s[20:21], s[42:43], 2
	v_readlane_b32 s10, v255, 1
	v_mov_b32_e32 v0, v196
	v_readlane_b32 s11, v255, 2
	s_add_u32 s20, s10, s20
	s_addc_u32 s21, s11, s21
	v_readfirstlane_b32 s23, v0
	s_ashr_i32 s23, s23, 8
	s_add_i32 s23, s23, s22
	s_min_i32 s23, s23, 0xff
	s_ashr_i32 s26, s23, 31
	s_lshr_b32 s26, s26, 28
	s_add_i32 s26, s23, s26
	s_and_b32 s27, s26, 0x3fffff0
	v_bfe_u32 v6, v4, 6, 2
	s_sub_i32 s23, s23, s27
	v_lshl_or_b32 v2, s23, 6, v6
	s_lshl_b32 s23, s26, 2
	s_and_b32 s26, s23, 0xffffffc0
	s_ashr_i32 s27, s26, 31
	s_lshl_b64 s[26:27], s[26:27], 2
	s_add_u32 s26, s20, s26
	v_lshlrev_b32_e32 v0, 2, v4
	s_waitcnt vmcnt(15)
	v_or_b32_e32 v10, 4, v2
	s_waitcnt vmcnt(13)
	v_or_b32_e32 v12, 8, v2
	s_waitcnt vmcnt(12)
	v_or_b32_e32 v14, 12, v2
	s_waitcnt vmcnt(0)
	v_or_b32_e32 v16, 16, v2
	v_or_b32_e32 v22, 20, v2
	v_or_b32_e32 v24, 24, v2
	v_or_b32_e32 v26, 28, v2
	s_addc_u32 s27, s21, s27
	v_and_b32_e32 v0, 0xfc, v0
	v_ashrrev_i32_e32 v3, 31, v2
	v_ashrrev_i32_e32 v11, 31, v10
	v_ashrrev_i32_e32 v13, 31, v12
	v_ashrrev_i32_e32 v15, 31, v14
	v_ashrrev_i32_e32 v17, 31, v16
	s_waitcnt lgkmcnt(4)
	v_ashrrev_i32_e32 v23, 31, v22
	v_ashrrev_i32_e32 v25, 31, v24
	v_ashrrev_i32_e32 v27, 31, v26
	v_lshl_add_u64 v[20:21], s[26:27], 0, v[0:1]
	v_lshlrev_b64 v[8:9], 12, v[2:3]
	v_lshlrev_b64 v[10:11], 12, v[10:11]
	v_lshlrev_b64 v[12:13], 12, v[12:13]
	v_lshlrev_b64 v[14:15], 12, v[14:15]
	v_lshlrev_b64 v[16:17], 12, v[16:17]
	v_lshlrev_b64 v[22:23], 12, v[22:23]
	v_lshlrev_b64 v[24:25], 12, v[24:25]
	v_lshlrev_b64 v[26:27], 12, v[26:27]
	v_lshl_add_u64 v[8:9], v[20:21], 0, v[8:9]
	v_lshl_add_u64 v[10:11], v[20:21], 0, v[10:11]
	v_lshl_add_u64 v[12:13], v[20:21], 0, v[12:13]
	v_lshl_add_u64 v[14:15], v[20:21], 0, v[14:15]
	v_lshl_add_u64 v[16:17], v[20:21], 0, v[16:17]
	v_lshl_add_u64 v[22:23], v[20:21], 0, v[22:23]
	v_lshl_add_u64 v[24:25], v[20:21], 0, v[24:25]
	v_lshl_add_u64 v[26:27], v[20:21], 0, v[26:27]
	global_load_dword v8, v[8:9], off nt
	s_nop 0
	global_load_dword v9, v[10:11], off nt
	s_nop 0
	global_load_dword v11, v[12:13], off nt
	s_nop 0
	global_load_dword v13, v[14:15], off nt
	s_nop 0
	global_load_dword v14, v[16:17], off nt
	global_load_dword v15, v[22:23], off nt
	s_nop 0
	global_load_dword v16, v[24:25], off nt
	global_load_dword v17, v[26:27], off nt
	v_or_b32_e32 v22, 32, v2
	v_or_b32_e32 v24, 36, v2
	v_or_b32_e32 v26, 40, v2
	v_ashrrev_i32_e32 v23, 31, v22
	v_ashrrev_i32_e32 v25, 31, v24
	v_ashrrev_i32_e32 v27, 31, v26
	v_or_b32_e32 v28, 44, v2
	v_or_b32_e32 v30, 48, v2
	s_waitcnt lgkmcnt(0)
	v_or_b32_e32 v32, 52, v2
	v_or_b32_e32 v34, 56, v2
	v_or_b32_e32 v2, 60, v2
	v_lshlrev_b64 v[22:23], 12, v[22:23]
	v_lshlrev_b64 v[24:25], 12, v[24:25]
	v_lshlrev_b64 v[26:27], 12, v[26:27]
	v_ashrrev_i32_e32 v29, 31, v28
	v_ashrrev_i32_e32 v31, 31, v30
	v_ashrrev_i32_e32 v33, 31, v32
	v_ashrrev_i32_e32 v35, 31, v34
	v_ashrrev_i32_e32 v3, 31, v2
	v_lshl_add_u64 v[22:23], v[20:21], 0, v[22:23]
	v_lshl_add_u64 v[24:25], v[20:21], 0, v[24:25]
	v_lshl_add_u64 v[26:27], v[20:21], 0, v[26:27]
	v_lshlrev_b64 v[28:29], 12, v[28:29]
	v_lshlrev_b64 v[30:31], 12, v[30:31]
	v_lshlrev_b64 v[32:33], 12, v[32:33]
	v_lshlrev_b64 v[34:35], 12, v[34:35]
	v_lshlrev_b64 v[2:3], 12, v[2:3]
	v_lshl_add_u64 v[28:29], v[20:21], 0, v[28:29]
	v_lshl_add_u64 v[30:31], v[20:21], 0, v[30:31]
	v_lshl_add_u64 v[32:33], v[20:21], 0, v[32:33]
	v_lshl_add_u64 v[34:35], v[20:21], 0, v[34:35]
	v_lshl_add_u64 v[2:3], v[20:21], 0, v[2:3]
	global_load_dword v19, v[22:23], off nt
	global_load_dword v20, v[24:25], off nt
	global_load_dword v21, v[26:27], off nt
	s_nop 0
	global_load_dword v22, v[28:29], off nt
	global_load_dword v23, v[30:31], off nt
	global_load_dword v24, v[32:33], off nt
	global_load_dword v25, v[34:35], off nt
	global_load_dword v26, v[2:3], off nt
	v_bfe_u32 v7, v4, 3, 5
	v_lshlrev_b32_e32 v4, 3, v4
	v_and_b32_e32 v10, 56, v4
	v_mul_u32_u24_e32 v12, 0x41, v10
	v_lshlrev_b32_e32 v12, 2, v12
	v_lshlrev_b32_e32 v27, 2, v7
	v_lshlrev_b32_e32 v4, 1, v10
	v_mov_b32_e32 v5, v1
	v_add3_u32 v12, s33, v12, v27
	v_mul_u32_u24_e32 v27, 0x104, v6
	v_lshl_add_u64 v[2:3], s[20:21], 0, v[0:1]
	v_lshl_add_u64 v[4:5], s[0:1], 0, v[4:5]
	v_or_b32_e32 v10, 32, v7
	v_add3_u32 v0, s33, v27, v0
	v_readlane_b32 s5, v254, 60
	v_readlane_b32 s6, v254, 61
	v_readlane_b32 s7, v254, 62
	v_readlane_b32 s8, v254, 63
	v_readlane_b32 s9, v255, 0
	v_readlane_b32 s12, v255, 3
	v_readlane_b32 s13, v255, 4
	v_readlane_b32 s14, v255, 5
	v_readlane_b32 s15, v255, 6
	v_readlane_b32 s16, v255, 7
	v_readlane_b32 s17, v255, 8
	v_readlane_b32 s18, v255, 9
	v_readlane_b32 s19, v255, 10
	s_branch .LBB0_1034

.LBB0_1036:
	v_mov_b32_e32 v4, v196
	v_readlane_b32 vcc_hi, v255, 44
	s_sub_i32 s0, s2, vcc_hi
	s_cmp_lt_i32 s0, 0
	s_cselect_b32 vcc_lo, s34, 0
	s_add_i32 s0, s0, vcc_lo
	s_add_i32 vcc_hi, vcc_hi, 128
	s_cmp_ge_u32 vcc_hi, s34
	s_cselect_b32 vcc_lo, s34, 0
	s_sub_i32 vcc_hi, vcc_hi, vcc_lo
	s_nop 0
	v_writelane_b32 v255, vcc_hi, 44
	v_mov_b32_e32 v0, v196
	s_lshl_b32 s0, s0, 1
	v_readfirstlane_b32 s1, v0
	s_ashr_i32 s1, s1, 8
	v_mov_b32_e32 v0, v196
	s_add_i32 s1, s1, s0
	s_nop 0
	v_readfirstlane_b32 s0, v0
	s_ashr_i32 s0, s0, 8
	s_sub_i32 s22, s1, s0
	s_cmpk_gt_i32 s22, 0x2ff
	s_cbranch_scc1 .LBB0_1041
	v_readlane_b32 s4, v253, 14
	s_mul_i32 s0, s40, 0x600000
	v_readlane_b32 s12, v253, 22
	v_readlane_b32 s13, v253, 23
	s_add_u32 s0, s12, s0
	s_addc_u32 s1, s13, 0
	s_mul_i32 s20, s40, 0xc00000
	v_mov_b32_e32 v0, v196
	s_add_u32 s20, s74, s20
	s_addc_u32 s21, s75, 0
	v_readfirstlane_b32 s23, v0
	s_ashr_i32 s23, s23, 8
	s_add_i32 s23, s23, s22
	s_min_i32 s23, s23, 0x2ff
	s_ashr_i32 s26, s23, 31
	s_lshr_b32 s26, s26, 28
	s_add_i32 s26, s23, s26
	s_and_b32 s27, s26, 0xfff0
	v_bfe_u32 v6, v4, 6, 2
	s_sub_i32 s23, s23, s27
	v_lshl_or_b32 v5, s23, 6, v6
	s_lshl_b32 s23, s26, 2
	s_and_b32 s26, s23, 0xffffffc0
	s_ashr_i32 s27, s26, 31
	s_lshl_b64 s[26:27], s[26:27], 2
	s_add_u32 s26, s20, s26
	v_lshlrev_b32_e32 v0, 2, v4
	s_addc_u32 s27, s21, s27
	v_and_b32_e32 v0, 0xfc, v0
	s_waitcnt vmcnt(1)
	v_mul_lo_u32 v8, v5, s47
	v_lshl_add_u64 v[2:3], s[26:27], 0, v[0:1]
	v_ashrrev_i32_e32 v9, 31, v8
	v_lshl_add_u64 v[2:3], v[8:9], 2, v[2:3]
	v_add_co_u32_e32 v10, vcc, s36, v2
	s_mov_b32 s4, 0x60000
	s_nop 0
	v_addc_co_u32_e32 v11, vcc, 0, v3, vcc
	v_add_co_u32_e32 v12, vcc, s35, v2
	s_mov_b32 s23, 0x6c000
	s_nop 0
	v_addc_co_u32_e32 v13, vcc, 0, v3, vcc
	v_add_co_u32_e32 v14, vcc, s51, v2
	v_bfe_u32 v7, v4, 3, 5
	s_nop 0
	v_addc_co_u32_e32 v15, vcc, 0, v3, vcc
	s_waitcnt vmcnt(0)
	v_add_co_u32_e32 v16, vcc, s52, v2
	v_lshlrev_b32_e32 v4, 3, v4
	s_nop 0
	v_addc_co_u32_e32 v17, vcc, 0, v3, vcc
	v_add_co_u32_e32 v20, vcc, s96, v2
	v_and_b32_e32 v9, 56, v4
	s_nop 0
	v_addc_co_u32_e32 v21, vcc, 0, v3, vcc
	v_add_co_u32_e32 v22, vcc, s46, v2
	v_lshlrev_b32_e32 v4, 1, v9
	s_waitcnt lgkmcnt(4)
	v_addc_co_u32_e32 v23, vcc, 0, v3, vcc
	v_add_co_u32_e32 v24, vcc, s97, v2
	v_mov_b32_e32 v5, v1
	s_nop 0
	v_addc_co_u32_e32 v25, vcc, 0, v3, vcc
	global_load_dword v8, v[2:3], off nt
	s_nop 0
	global_load_dword v10, v[10:11], off nt
	s_nop 0
	global_load_dword v12, v[12:13], off nt
	s_nop 0
	global_load_dword v13, v[14:15], off nt
	s_nop 0
	global_load_dword v14, v[16:17], off nt
	global_load_dword v15, v[20:21], off nt
	s_nop 0
	global_load_dword v16, v[22:23], off nt
	global_load_dword v17, v[24:25], off nt
	v_add_co_u32_e32 v20, vcc, s4, v2
	s_mov_b32 s4, 0x84000
	s_nop 0
	v_addc_co_u32_e32 v21, vcc, 0, v3, vcc
	v_add_co_u32_e32 v22, vcc, s23, v2
	s_mov_b32 s23, 0x78000
	s_nop 0
	v_addc_co_u32_e32 v23, vcc, 0, v3, vcc
	v_add_co_u32_e32 v24, vcc, s23, v2
	s_mov_b32 s23, 0x90000
	s_nop 0
	v_addc_co_u32_e32 v25, vcc, 0, v3, vcc
	v_add_co_u32_e32 v26, vcc, s4, v2
	s_mov_b32 s4, 0x9c000
	s_nop 0
	v_addc_co_u32_e32 v27, vcc, 0, v3, vcc
	v_add_co_u32_e32 v28, vcc, s23, v2
	s_mov_b32 s23, 0xa8000
	s_nop 0
	v_addc_co_u32_e32 v29, vcc, 0, v3, vcc
	v_add_co_u32_e32 v30, vcc, s4, v2
	v_mul_u32_u24_e32 v11, 0x41, v9
	s_nop 0
	v_addc_co_u32_e32 v31, vcc, 0, v3, vcc
	s_waitcnt lgkmcnt(0)
	v_add_co_u32_e32 v32, vcc, s23, v2
	s_mov_b32 s23, 0xb4000
	s_nop 0
	v_addc_co_u32_e32 v33, vcc, 0, v3, vcc
	v_add_co_u32_e32 v2, vcc, s23, v2
	v_lshlrev_b32_e32 v11, 2, v11
	s_nop 0
	v_addc_co_u32_e32 v3, vcc, 0, v3, vcc
	global_load_dword v19, v[20:21], off nt
	s_nop 0
	global_load_dword v20, v[22:23], off nt
	global_load_dword v21, v[24:25], off nt
	s_nop 0
	global_load_dword v22, v[26:27], off nt
	global_load_dword v23, v[28:29], off nt
	global_load_dword v24, v[30:31], off nt
	global_load_dword v25, v[32:33], off nt
	s_nop 0
	global_load_dword v26, v[2:3], off nt
	v_lshlrev_b32_e32 v27, 2, v7
	v_add3_u32 v11, s33, v11, v27
	v_mul_u32_u24_e32 v27, 0x104, v6
	v_lshl_add_u64 v[2:3], s[20:21], 0, v[0:1]
	v_lshl_add_u64 v[4:5], s[0:1], 0, v[4:5]
	v_or_b32_e32 v9, 32, v7
	v_add3_u32 v0, s33, v27, v0
	v_readlane_b32 s5, v253, 15
	v_readlane_b32 s6, v253, 16
	v_readlane_b32 s7, v253, 17
	v_readlane_b32 s8, v253, 18
	v_readlane_b32 s9, v253, 19
	v_readlane_b32 s10, v253, 20
	v_readlane_b32 s11, v253, 21
	v_readlane_b32 s14, v253, 24
	v_readlane_b32 s15, v253, 25
	v_readlane_b32 s16, v253, 26
	v_readlane_b32 s17, v253, 27
	v_readlane_b32 s18, v253, 28
	v_readlane_b32 s19, v253, 29
	s_branch .LBB0_1039

.LBB0_1041:
	v_mov_b32_e32 v4, v196
	v_readlane_b32 vcc_hi, v255, 44
	s_sub_i32 s0, s2, vcc_hi
	s_cmp_lt_i32 s0, 0
	s_cselect_b32 vcc_lo, s34, 0
	s_add_i32 s0, s0, vcc_lo
	s_add_i32 vcc_hi, vcc_hi, 128
	s_cmp_ge_u32 vcc_hi, s34
	s_cselect_b32 vcc_lo, s34, 0
	s_sub_i32 vcc_hi, vcc_hi, vcc_lo
	s_nop 0
	v_writelane_b32 v255, vcc_hi, 44
	v_mov_b32_e32 v0, v196
	s_lshl_b32 s0, s0, 1
	v_readfirstlane_b32 s1, v0
	s_ashr_i32 s1, s1, 8
	v_mov_b32_e32 v0, v196
	s_add_i32 s1, s1, s0
	s_nop 0
	v_readfirstlane_b32 s0, v0
	s_ashr_i32 s0, s0, 8
	s_sub_i32 s22, s1, s0
	s_cmpk_gt_i32 s22, 0xff
	s_cbranch_scc1 .LBB0_1025
	v_readlane_b32 s4, v253, 14
	s_lshl_b64 s[0:1], s[42:43], 1
	v_readlane_b32 s14, v253, 24
	v_readlane_b32 s15, v253, 25
	s_add_u32 s0, s14, s0
	s_addc_u32 s1, s15, s1
	s_lshl_b64 s[20:21], s[42:43], 2
	v_mov_b32_e32 v0, v196
	s_add_u32 s20, s68, s20
	s_addc_u32 s21, s69, s21
	v_readfirstlane_b32 s23, v0
	s_ashr_i32 s23, s23, 8
	s_add_i32 s23, s23, s22
	s_min_i32 s23, s23, 0xff
	s_ashr_i32 s26, s23, 31
	s_lshr_b32 s26, s26, 28
	s_add_i32 s26, s23, s26
	s_and_b32 s27, s26, 0x3fffff0
	v_bfe_u32 v6, v4, 6, 2
	s_sub_i32 s23, s23, s27
	v_lshl_or_b32 v2, s23, 6, v6
	s_lshl_b32 s23, s26, 2
	s_and_b32 s26, s23, 0xffffffc0
	s_ashr_i32 s27, s26, 31
	s_lshl_b64 s[26:27], s[26:27], 2
	s_add_u32 s26, s20, s26
	v_lshlrev_b32_e32 v0, 2, v4
	s_waitcnt vmcnt(15)
	v_or_b32_e32 v10, 4, v2
	s_waitcnt vmcnt(13)
	v_or_b32_e32 v12, 8, v2
	s_waitcnt vmcnt(12)
	v_or_b32_e32 v14, 12, v2
	s_waitcnt vmcnt(0)
	v_or_b32_e32 v16, 16, v2
	v_or_b32_e32 v22, 20, v2
	v_or_b32_e32 v24, 24, v2
	v_or_b32_e32 v26, 28, v2
	s_addc_u32 s27, s21, s27
	v_and_b32_e32 v0, 0xfc, v0
	v_ashrrev_i32_e32 v3, 31, v2
	v_ashrrev_i32_e32 v11, 31, v10
	v_ashrrev_i32_e32 v13, 31, v12
	v_ashrrev_i32_e32 v15, 31, v14
	v_ashrrev_i32_e32 v17, 31, v16
	s_waitcnt lgkmcnt(4)
	v_ashrrev_i32_e32 v23, 31, v22
	v_ashrrev_i32_e32 v25, 31, v24
	v_ashrrev_i32_e32 v27, 31, v26
	v_lshl_add_u64 v[20:21], s[26:27], 0, v[0:1]
	v_lshlrev_b64 v[8:9], 12, v[2:3]
	v_lshlrev_b64 v[10:11], 12, v[10:11]
	v_lshlrev_b64 v[12:13], 12, v[12:13]
	v_lshlrev_b64 v[14:15], 12, v[14:15]
	v_lshlrev_b64 v[16:17], 12, v[16:17]
	v_lshlrev_b64 v[22:23], 12, v[22:23]
	v_lshlrev_b64 v[24:25], 12, v[24:25]
	v_lshlrev_b64 v[26:27], 12, v[26:27]
	v_lshl_add_u64 v[8:9], v[20:21], 0, v[8:9]
	v_lshl_add_u64 v[10:11], v[20:21], 0, v[10:11]
	v_lshl_add_u64 v[12:13], v[20:21], 0, v[12:13]
	v_lshl_add_u64 v[14:15], v[20:21], 0, v[14:15]
	v_lshl_add_u64 v[16:17], v[20:21], 0, v[16:17]
	v_lshl_add_u64 v[22:23], v[20:21], 0, v[22:23]
	v_lshl_add_u64 v[24:25], v[20:21], 0, v[24:25]
	v_lshl_add_u64 v[26:27], v[20:21], 0, v[26:27]
	global_load_dword v8, v[8:9], off nt
	s_nop 0
	global_load_dword v9, v[10:11], off nt
	s_nop 0
	global_load_dword v11, v[12:13], off nt
	s_nop 0
	global_load_dword v13, v[14:15], off nt
	s_nop 0
	global_load_dword v14, v[16:17], off nt
	global_load_dword v15, v[22:23], off nt
	s_nop 0
	global_load_dword v16, v[24:25], off nt
	global_load_dword v17, v[26:27], off nt
	v_or_b32_e32 v22, 32, v2
	v_or_b32_e32 v24, 36, v2
	v_or_b32_e32 v26, 40, v2
	v_ashrrev_i32_e32 v23, 31, v22
	v_ashrrev_i32_e32 v25, 31, v24
	v_ashrrev_i32_e32 v27, 31, v26
	v_or_b32_e32 v28, 44, v2
	v_or_b32_e32 v30, 48, v2
	s_waitcnt lgkmcnt(0)
	v_or_b32_e32 v32, 52, v2
	v_or_b32_e32 v34, 56, v2
	v_or_b32_e32 v2, 60, v2
	v_lshlrev_b64 v[22:23], 12, v[22:23]
	v_lshlrev_b64 v[24:25], 12, v[24:25]
	v_lshlrev_b64 v[26:27], 12, v[26:27]
	v_ashrrev_i32_e32 v29, 31, v28
	v_ashrrev_i32_e32 v31, 31, v30
	v_ashrrev_i32_e32 v33, 31, v32
	v_ashrrev_i32_e32 v35, 31, v34
	v_ashrrev_i32_e32 v3, 31, v2
	v_lshl_add_u64 v[22:23], v[20:21], 0, v[22:23]
	v_lshl_add_u64 v[24:25], v[20:21], 0, v[24:25]
	v_lshl_add_u64 v[26:27], v[20:21], 0, v[26:27]
	v_lshlrev_b64 v[28:29], 12, v[28:29]
	v_lshlrev_b64 v[30:31], 12, v[30:31]
	v_lshlrev_b64 v[32:33], 12, v[32:33]
	v_lshlrev_b64 v[34:35], 12, v[34:35]
	v_lshlrev_b64 v[2:3], 12, v[2:3]
	v_lshl_add_u64 v[28:29], v[20:21], 0, v[28:29]
	v_lshl_add_u64 v[30:31], v[20:21], 0, v[30:31]
	v_lshl_add_u64 v[32:33], v[20:21], 0, v[32:33]
	v_lshl_add_u64 v[34:35], v[20:21], 0, v[34:35]
	v_lshl_add_u64 v[2:3], v[20:21], 0, v[2:3]
	global_load_dword v19, v[22:23], off nt
	global_load_dword v20, v[24:25], off nt
	global_load_dword v21, v[26:27], off nt
	s_nop 0
	global_load_dword v22, v[28:29], off nt
	global_load_dword v23, v[30:31], off nt
	global_load_dword v24, v[32:33], off nt
	global_load_dword v25, v[34:35], off nt
	global_load_dword v26, v[2:3], off nt
	v_bfe_u32 v7, v4, 3, 5
	v_lshlrev_b32_e32 v4, 3, v4
	v_and_b32_e32 v10, 56, v4
	v_mul_u32_u24_e32 v12, 0x41, v10
	v_lshlrev_b32_e32 v12, 2, v12
	v_lshlrev_b32_e32 v27, 2, v7
	v_lshlrev_b32_e32 v4, 1, v10
	v_mov_b32_e32 v5, v1
	v_add3_u32 v12, s33, v12, v27
	v_mul_u32_u24_e32 v27, 0x104, v6
	v_lshl_add_u64 v[2:3], s[20:21], 0, v[0:1]
	v_lshl_add_u64 v[4:5], s[0:1], 0, v[4:5]
	v_or_b32_e32 v10, 32, v7
	v_add3_u32 v0, s33, v27, v0
	v_readlane_b32 s5, v253, 15
	v_readlane_b32 s6, v253, 16
	v_readlane_b32 s7, v253, 17
	v_readlane_b32 s8, v253, 18
	v_readlane_b32 s9, v253, 19
	v_readlane_b32 s10, v253, 20
	v_readlane_b32 s11, v253, 21
	v_readlane_b32 s12, v253, 22
	v_readlane_b32 s13, v253, 23
	v_readlane_b32 s16, v253, 26
	v_readlane_b32 s17, v253, 27
	v_readlane_b32 s18, v253, 28
	v_readlane_b32 s19, v253, 29
	s_branch .LBB0_1044

.LBB0_1058:
	v_mov_b32_e32 v4, v196
	v_readlane_b32 vcc_hi, v255, 44
	s_sub_i32 s0, s2, vcc_hi
	s_cmp_lt_i32 s0, 0
	s_cselect_b32 vcc_lo, s34, 0
	s_add_i32 s0, s0, vcc_lo
	s_add_i32 vcc_hi, vcc_hi, 96
	s_cmp_ge_u32 vcc_hi, s34
	s_cselect_b32 vcc_lo, s34, 0
	s_sub_i32 vcc_hi, vcc_hi, vcc_lo
	s_nop 0
	v_writelane_b32 v255, vcc_hi, 44
	v_mov_b32_e32 v0, v196
	s_lshl_b32 s0, s0, 1
	v_readfirstlane_b32 s20, v0
	s_ashr_i32 s20, s20, 8
	v_mov_b32_e32 v0, v196
	s_add_i32 s20, s20, s0
	s_mul_hi_u32 s29, s26, 0x2c0000
	v_readfirstlane_b32 s0, v0
	s_ashr_i32 s0, s0, 8
	s_sub_i32 s27, s20, s0
	s_mul_i32 s28, s26, 0x2c0000
	s_mul_hi_u32 s1, s26, 0x580000
	s_cmpk_gt_i32 s27, 0x2bf
	s_mul_i32 s0, s26, 0x580000
	s_cbranch_scc1 .LBB0_1063
	v_readlane_b32 s4, v253, 14
	s_lshl_b64 s[20:21], s[0:1], 1
	v_readlane_b32 s16, v253, 26
	v_readlane_b32 s5, v253, 15
	v_readlane_b32 s6, v253, 16
	v_readlane_b32 s7, v253, 17
	v_readlane_b32 s8, v253, 18
	v_readlane_b32 s9, v253, 19
	v_readlane_b32 s10, v253, 20
	v_readlane_b32 s11, v253, 21
	v_readlane_b32 s12, v253, 22
	v_readlane_b32 s13, v253, 23
	v_readlane_b32 s14, v253, 24
	v_readlane_b32 s15, v253, 25
	v_readlane_b32 s17, v253, 27
	v_readlane_b32 s18, v253, 28
	v_readlane_b32 s19, v253, 29
	s_add_u32 s20, s16, s20
	s_addc_u32 s21, s17, s21
	v_readlane_b32 s4, v254, 27
	s_lshl_b64 s[22:23], s[28:29], 2
	v_readlane_b32 s16, v254, 39
	v_mov_b32_e32 v0, v196
	v_readlane_b32 s17, v254, 40
	s_add_u32 s22, s16, s22
	s_addc_u32 s23, s17, s23
	v_readfirstlane_b32 s40, v0
	s_ashr_i32 s40, s40, 8
	s_add_i32 s40, s40, s27
	s_min_i32 s40, s40, 0x2bf
	s_ashr_i32 s41, s40, 31
	s_lshr_b32 s41, s41, 28
	s_add_i32 s41, s40, s41
	s_and_b32 s42, s41, 0x3fff0
	v_bfe_u32 v6, v4, 6, 2
	s_sub_i32 s40, s40, s42
	v_lshl_or_b32 v5, s40, 6, v6
	s_lshl_b32 s40, s41, 2
	s_andn2_b32 s40, s40, 63
	s_ashr_i32 s41, s40, 31
	s_lshl_b64 s[40:41], s[40:41], 2
	s_add_u32 s40, s22, s40
	v_lshlrev_b32_e32 v0, 2, v4
	s_addc_u32 s41, s23, s41
	v_and_b32_e32 v0, 0xfc, v0
	s_waitcnt vmcnt(1)
	v_mul_lo_u32 v8, v5, s49
	v_lshl_add_u64 v[2:3], s[40:41], 0, v[0:1]
	v_ashrrev_i32_e32 v9, 31, v8
	v_lshl_add_u64 v[2:3], v[8:9], 2, v[2:3]
	v_add_co_u32_e32 v10, vcc, s43, v2
	s_mov_b32 s4, 0x63000
	s_nop 0
	v_addc_co_u32_e32 v11, vcc, 0, v3, vcc
	v_add_co_u32_e32 v12, vcc, s44, v2
	v_bfe_u32 v7, v4, 3, 5
	s_nop 0
	v_addc_co_u32_e32 v13, vcc, 0, v3, vcc
	v_add_co_u32_e32 v14, vcc, s45, v2
	v_lshlrev_b32_e32 v4, 3, v4
	s_nop 0
	v_addc_co_u32_e32 v15, vcc, 0, v3, vcc
	s_waitcnt vmcnt(0)
	v_add_co_u32_e32 v16, vcc, s47, v2
	v_mov_b32_e32 v5, v1
	s_nop 0
	v_addc_co_u32_e32 v17, vcc, 0, v3, vcc
	v_add_co_u32_e32 v20, vcc, s48, v2
	v_readlane_b32 s5, v254, 28
	s_nop 0
	v_addc_co_u32_e32 v21, vcc, 0, v3, vcc
	v_add_co_u32_e32 v22, vcc, s38, v2
	v_readlane_b32 s6, v254, 29
	s_waitcnt lgkmcnt(4)
	v_addc_co_u32_e32 v23, vcc, 0, v3, vcc
	v_add_co_u32_e32 v24, vcc, s50, v2
	v_readlane_b32 s7, v254, 30
	s_nop 0
	v_addc_co_u32_e32 v25, vcc, 0, v3, vcc
	global_load_dword v8, v[2:3], off nt
	global_load_dword v9, v[10:11], off nt
	s_nop 0
	global_load_dword v11, v[12:13], off nt
	s_nop 0
	global_load_dword v13, v[14:15], off nt
	s_nop 0
	global_load_dword v14, v[16:17], off nt
	global_load_dword v15, v[20:21], off nt
	s_nop 0
	global_load_dword v16, v[22:23], off nt
	global_load_dword v17, v[24:25], off nt
	v_add_co_u32_e32 v20, vcc, s51, v2
	v_and_b32_e32 v10, 56, v4
	s_nop 0
	v_addc_co_u32_e32 v21, vcc, 0, v3, vcc
	v_add_co_u32_e32 v22, vcc, s4, v2
	s_mov_b32 s4, 0x6e000
	s_nop 0
	v_addc_co_u32_e32 v23, vcc, 0, v3, vcc
	v_add_co_u32_e32 v24, vcc, s4, v2
	s_mov_b32 s4, 0x79000
	s_nop 0
	v_addc_co_u32_e32 v25, vcc, 0, v3, vcc
	v_add_co_u32_e32 v26, vcc, s4, v2
	s_mov_b32 s4, 0x8f000
	s_nop 0
	v_addc_co_u32_e32 v27, vcc, 0, v3, vcc
	v_add_co_u32_e32 v28, vcc, s46, v2
	v_mul_u32_u24_e32 v12, 0x41, v10
	s_nop 0
	v_addc_co_u32_e32 v29, vcc, 0, v3, vcc
	v_add_co_u32_e32 v30, vcc, s4, v2
	s_mov_b32 s4, 0x9a000
	s_nop 0
	v_addc_co_u32_e32 v31, vcc, 0, v3, vcc
	s_waitcnt lgkmcnt(0)
	v_add_co_u32_e32 v32, vcc, s4, v2
	s_mov_b32 s4, 0xa5000
	s_nop 0
	v_addc_co_u32_e32 v33, vcc, 0, v3, vcc
	v_add_co_u32_e32 v2, vcc, s4, v2
	v_lshlrev_b32_e32 v12, 2, v12
	s_nop 0
	v_addc_co_u32_e32 v3, vcc, 0, v3, vcc
	global_load_dword v19, v[20:21], off nt
	s_nop 0
	global_load_dword v20, v[22:23], off nt
	global_load_dword v21, v[24:25], off nt
	s_nop 0
	global_load_dword v22, v[26:27], off nt
	global_load_dword v23, v[28:29], off nt
	global_load_dword v24, v[30:31], off nt
	global_load_dword v25, v[32:33], off nt
	s_nop 0
	global_load_dword v26, v[2:3], off nt
	v_lshlrev_b32_e32 v27, 2, v7
	v_lshlrev_b32_e32 v4, 1, v10
	v_add3_u32 v12, s33, v12, v27
	v_mul_u32_u24_e32 v27, 0x104, v6
	v_lshl_add_u64 v[2:3], s[22:23], 0, v[0:1]
	v_lshl_add_u64 v[4:5], s[20:21], 0, v[4:5]
	v_or_b32_e32 v10, 32, v7
	v_add3_u32 v0, s33, v27, v0
	v_readlane_b32 s8, v254, 31
	v_readlane_b32 s9, v254, 32
	v_readlane_b32 s10, v254, 33
	v_readlane_b32 s11, v254, 34
	v_readlane_b32 s12, v254, 35
	v_readlane_b32 s13, v254, 36
	v_readlane_b32 s14, v254, 37
	v_readlane_b32 s15, v254, 38
	v_readlane_b32 s18, v254, 41
	v_readlane_b32 s19, v254, 42
	s_branch .LBB0_1061

.LBB0_1063:
	v_mov_b32_e32 v4, v196
	v_readlane_b32 vcc_hi, v255, 44
	s_sub_i32 s20, s2, vcc_hi
	s_cmp_lt_i32 s20, 0
	s_cselect_b32 vcc_lo, s34, 0
	s_add_i32 s20, s20, vcc_lo
	s_add_i32 vcc_hi, vcc_hi, 96
	s_cmp_ge_u32 vcc_hi, s34
	s_cselect_b32 vcc_lo, s34, 0
	s_sub_i32 vcc_hi, vcc_hi, vcc_lo
	s_nop 0
	v_writelane_b32 v255, vcc_hi, 44
	v_mov_b32_e32 v0, v196
	s_lshl_b32 s20, s20, 1
	v_readfirstlane_b32 s21, v0
	s_ashr_i32 s21, s21, 8
	v_mov_b32_e32 v0, v196
	s_add_i32 s21, s21, s20
	s_nop 0
	v_readfirstlane_b32 s20, v0
	s_ashr_i32 s20, s20, 8
	s_sub_i32 s22, s21, s20
	s_cmpk_gt_i32 s22, 0x2bf
	s_cbranch_scc1 .LBB0_1068
	v_readlane_b32 s4, v253, 14
	s_lshl_b64 s[0:1], s[0:1], 1
	v_readlane_b32 s16, v253, 26
	v_readlane_b32 s5, v253, 15
	v_readlane_b32 s6, v253, 16
	v_readlane_b32 s7, v253, 17
	v_readlane_b32 s8, v253, 18
	v_readlane_b32 s9, v253, 19
	v_readlane_b32 s10, v253, 20
	v_readlane_b32 s11, v253, 21
	v_readlane_b32 s12, v253, 22
	v_readlane_b32 s13, v253, 23
	v_readlane_b32 s14, v253, 24
	v_readlane_b32 s15, v253, 25
	v_readlane_b32 s17, v253, 27
	v_readlane_b32 s18, v253, 28
	v_readlane_b32 s19, v253, 29
	s_add_u32 s0, s16, s0
	s_addc_u32 s1, s17, s1
	v_readlane_b32 s4, v254, 27
	s_lshl_b64 s[20:21], s[28:29], 2
	v_readlane_b32 s18, v254, 41
	v_mov_b32_e32 v0, v196
	v_readlane_b32 s19, v254, 42
	s_add_u32 s20, s18, s20
	s_addc_u32 s21, s19, s21
	v_readfirstlane_b32 s23, v0
	s_ashr_i32 s23, s23, 8
	s_add_i32 s23, s23, s22
	s_min_i32 s23, s23, 0x2bf
	s_ashr_i32 s27, s23, 31
	s_lshr_b32 s27, s27, 28
	s_add_i32 s27, s23, s27
	s_and_b32 s40, s27, 0x3fff0
	v_bfe_u32 v6, v4, 6, 2
	s_sub_i32 s23, s23, s40
	v_lshl_or_b32 v5, s23, 6, v6
	s_lshl_b32 s23, s27, 2
	s_and_b32 s40, s23, 0xffffffc0
	s_ashr_i32 s41, s40, 31
	s_lshl_b64 s[40:41], s[40:41], 2
	s_add_u32 s40, s20, s40
	v_lshlrev_b32_e32 v0, 2, v4
	s_addc_u32 s41, s21, s41
	v_and_b32_e32 v0, 0xfc, v0
	s_waitcnt vmcnt(1)
	v_mul_lo_u32 v8, v5, s49
	v_lshl_add_u64 v[2:3], s[40:41], 0, v[0:1]
	v_ashrrev_i32_e32 v9, 31, v8
	v_lshl_add_u64 v[2:3], v[8:9], 2, v[2:3]
	v_add_co_u32_e32 v10, vcc, s43, v2
	s_mov_b32 s4, 0x63000
	s_nop 0
	v_addc_co_u32_e32 v11, vcc, 0, v3, vcc
	v_add_co_u32_e32 v12, vcc, s44, v2
	v_bfe_u32 v7, v4, 3, 5
	s_nop 0
	v_addc_co_u32_e32 v13, vcc, 0, v3, vcc
	v_add_co_u32_e32 v14, vcc, s45, v2
	v_lshlrev_b32_e32 v4, 3, v4
	s_nop 0
	v_addc_co_u32_e32 v15, vcc, 0, v3, vcc
	s_waitcnt vmcnt(0)
	v_add_co_u32_e32 v16, vcc, s47, v2
	v_mov_b32_e32 v5, v1
	s_nop 0
	v_addc_co_u32_e32 v17, vcc, 0, v3, vcc
	v_add_co_u32_e32 v20, vcc, s48, v2
	v_readlane_b32 s5, v254, 28
	s_nop 0
	v_addc_co_u32_e32 v21, vcc, 0, v3, vcc
	v_add_co_u32_e32 v22, vcc, s38, v2
	v_readlane_b32 s6, v254, 29
	s_waitcnt lgkmcnt(4)
	v_addc_co_u32_e32 v23, vcc, 0, v3, vcc
	v_add_co_u32_e32 v24, vcc, s50, v2
	v_readlane_b32 s7, v254, 30
	s_nop 0
	v_addc_co_u32_e32 v25, vcc, 0, v3, vcc
	global_load_dword v8, v[2:3], off nt
	global_load_dword v9, v[10:11], off nt
	s_nop 0
	global_load_dword v11, v[12:13], off nt
	s_nop 0
	global_load_dword v13, v[14:15], off nt
	s_nop 0
	global_load_dword v14, v[16:17], off nt
	global_load_dword v15, v[20:21], off nt
	s_nop 0
	global_load_dword v16, v[22:23], off nt
	global_load_dword v17, v[24:25], off nt
	v_add_co_u32_e32 v20, vcc, s51, v2
	v_and_b32_e32 v10, 56, v4
	s_nop 0
	v_addc_co_u32_e32 v21, vcc, 0, v3, vcc
	v_add_co_u32_e32 v22, vcc, s4, v2
	s_mov_b32 s4, 0x6e000
	s_nop 0
	v_addc_co_u32_e32 v23, vcc, 0, v3, vcc
	v_add_co_u32_e32 v24, vcc, s4, v2
	s_mov_b32 s4, 0x79000
	s_nop 0
	v_addc_co_u32_e32 v25, vcc, 0, v3, vcc
	v_add_co_u32_e32 v26, vcc, s4, v2
	s_mov_b32 s4, 0x8f000
	s_nop 0
	v_addc_co_u32_e32 v27, vcc, 0, v3, vcc
	v_add_co_u32_e32 v28, vcc, s46, v2
	v_mul_u32_u24_e32 v12, 0x41, v10
	s_nop 0
	v_addc_co_u32_e32 v29, vcc, 0, v3, vcc
	v_add_co_u32_e32 v30, vcc, s4, v2
	s_mov_b32 s4, 0x9a000
	s_nop 0
	v_addc_co_u32_e32 v31, vcc, 0, v3, vcc
	s_waitcnt lgkmcnt(0)
	v_add_co_u32_e32 v32, vcc, s4, v2
	s_mov_b32 s4, 0xa5000
	s_nop 0
	v_addc_co_u32_e32 v33, vcc, 0, v3, vcc
	v_add_co_u32_e32 v2, vcc, s4, v2
	v_lshlrev_b32_e32 v12, 2, v12
	s_nop 0
	v_addc_co_u32_e32 v3, vcc, 0, v3, vcc
	global_load_dword v19, v[20:21], off nt
	s_nop 0
	global_load_dword v20, v[22:23], off nt
	global_load_dword v21, v[24:25], off nt
	s_nop 0
	global_load_dword v22, v[26:27], off nt
	global_load_dword v23, v[28:29], off nt
	global_load_dword v24, v[30:31], off nt
	global_load_dword v25, v[32:33], off nt
	s_nop 0
	global_load_dword v26, v[2:3], off nt
	v_lshlrev_b32_e32 v27, 2, v7
	v_lshlrev_b32_e32 v4, 1, v10
	v_add3_u32 v12, s33, v12, v27
	v_mul_u32_u24_e32 v27, 0x104, v6
	v_lshl_add_u64 v[2:3], s[20:21], 0, v[0:1]
	v_lshl_add_u64 v[4:5], s[0:1], 0, v[4:5]
	v_or_b32_e32 v10, 32, v7
	v_add3_u32 v0, s33, v27, v0
	v_readlane_b32 s8, v254, 31
	v_readlane_b32 s9, v254, 32
	v_readlane_b32 s10, v254, 33
	v_readlane_b32 s11, v254, 34
	v_readlane_b32 s12, v254, 35
	v_readlane_b32 s13, v254, 36
	v_readlane_b32 s14, v254, 37
	v_readlane_b32 s15, v254, 38
	v_readlane_b32 s16, v254, 39
	v_readlane_b32 s17, v254, 40
	s_branch .LBB0_1066

.LBB0_1068:
	v_mov_b32_e32 v4, v196
	v_readlane_b32 vcc_hi, v255, 44
	s_sub_i32 s0, s2, vcc_hi
	s_cmp_lt_i32 s0, 0
	s_cselect_b32 vcc_lo, s34, 0
	s_add_i32 s0, s0, vcc_lo
	s_add_i32 vcc_hi, vcc_hi, 96
	s_cmp_ge_u32 vcc_hi, s34
	s_cselect_b32 vcc_lo, s34, 0
	s_sub_i32 vcc_hi, vcc_hi, vcc_lo
	s_nop 0
	v_writelane_b32 v255, vcc_hi, 44
	v_mov_b32_e32 v0, v196
	s_lshl_b32 s0, s0, 1
	v_readfirstlane_b32 s1, v0
	s_ashr_i32 s1, s1, 8
	v_mov_b32_e32 v0, v196
	s_add_i32 s1, s1, s0
	s_nop 0
	v_readfirstlane_b32 s0, v0
	s_ashr_i32 s0, s0, 8
	s_sub_i32 s22, s1, s0
	s_cmpk_gt_i32 s22, 0x2bf
	s_cbranch_scc1 .LBB0_1057
	v_readlane_b32 s4, v253, 14
	s_lshl_b64 s[0:1], s[28:29], 1
	v_readlane_b32 s18, v253, 28
	v_readlane_b32 s5, v253, 15
	v_readlane_b32 s6, v253, 16
	v_readlane_b32 s7, v253, 17
	v_readlane_b32 s8, v253, 18
	v_readlane_b32 s9, v253, 19
	v_readlane_b32 s10, v253, 20
	v_readlane_b32 s11, v253, 21
	v_readlane_b32 s12, v253, 22
	v_readlane_b32 s13, v253, 23
	v_readlane_b32 s14, v253, 24
	v_readlane_b32 s15, v253, 25
	v_readlane_b32 s16, v253, 26
	v_readlane_b32 s17, v253, 27
	v_readlane_b32 s19, v253, 29
	s_add_u32 s0, s18, s0
	s_addc_u32 s1, s19, s1
	s_mul_i32 s20, s26, 0xb00000
	v_readlane_b32 s4, v254, 59
	v_mov_b32_e32 v0, v196
	s_mul_hi_u32 s21, s26, 0xb00000
	v_readlane_b32 s5, v254, 60
	s_add_u32 s20, s4, s20
	s_addc_u32 s21, s5, s21
	v_readfirstlane_b32 s23, v0
	s_ashr_i32 s23, s23, 8
	s_add_i32 s23, s23, s22
	s_min_i32 s23, s23, 0x2bf
	s_mul_hi_i32 s27, s23, 0x2e8ba2e9
	s_lshr_b32 s28, s27, 31
	s_ashr_i32 s27, s27, 3
	s_add_i32 s27, s27, s28
	s_mul_i32 s28, s27, 44
	s_sub_i32 s23, s23, s28
	s_lshl_b32 s28, s27, 6
	v_bfe_u32 v6, v4, 6, 2
	s_ashr_i32 s29, s28, 31
	v_lshl_or_b32 v2, s23, 6, v6
	s_lshl_b64 s[28:29], s[28:29], 2
	s_add_u32 s28, s20, s28
	v_lshlrev_b32_e32 v0, 2, v4
	s_waitcnt vmcnt(15)
	v_or_b32_e32 v10, 4, v2
	s_waitcnt vmcnt(13)
	v_or_b32_e32 v12, 8, v2
	s_waitcnt vmcnt(12)
	v_or_b32_e32 v14, 12, v2
	s_waitcnt vmcnt(0)
	v_or_b32_e32 v16, 16, v2
	v_or_b32_e32 v22, 20, v2
	v_or_b32_e32 v24, 24, v2
	v_or_b32_e32 v26, 28, v2
	s_addc_u32 s29, s21, s29
	v_and_b32_e32 v0, 0xfc, v0
	v_ashrrev_i32_e32 v3, 31, v2
	v_ashrrev_i32_e32 v11, 31, v10
	v_ashrrev_i32_e32 v13, 31, v12
	v_ashrrev_i32_e32 v15, 31, v14
	v_ashrrev_i32_e32 v17, 31, v16
	s_waitcnt lgkmcnt(4)
	v_ashrrev_i32_e32 v23, 31, v22
	v_ashrrev_i32_e32 v25, 31, v24
	v_ashrrev_i32_e32 v27, 31, v26
	v_lshl_add_u64 v[20:21], s[28:29], 0, v[0:1]
	v_lshlrev_b64 v[8:9], 12, v[2:3]
	v_lshlrev_b64 v[10:11], 12, v[10:11]
	v_lshlrev_b64 v[12:13], 12, v[12:13]
	v_lshlrev_b64 v[14:15], 12, v[14:15]
	v_lshlrev_b64 v[16:17], 12, v[16:17]
	v_lshlrev_b64 v[22:23], 12, v[22:23]
	v_lshlrev_b64 v[24:25], 12, v[24:25]
	v_lshlrev_b64 v[26:27], 12, v[26:27]
	v_lshl_add_u64 v[8:9], v[20:21], 0, v[8:9]
	v_lshl_add_u64 v[10:11], v[20:21], 0, v[10:11]
	v_lshl_add_u64 v[12:13], v[20:21], 0, v[12:13]
	v_lshl_add_u64 v[14:15], v[20:21], 0, v[14:15]
	v_lshl_add_u64 v[16:17], v[20:21], 0, v[16:17]
	v_lshl_add_u64 v[22:23], v[20:21], 0, v[22:23]
	v_lshl_add_u64 v[24:25], v[20:21], 0, v[24:25]
	v_lshl_add_u64 v[26:27], v[20:21], 0, v[26:27]
	global_load_dword v8, v[8:9], off nt
	s_nop 0
	global_load_dword v9, v[10:11], off nt
	s_nop 0
	global_load_dword v11, v[12:13], off nt
	s_nop 0
	global_load_dword v13, v[14:15], off nt
	s_nop 0
	global_load_dword v14, v[16:17], off nt
	global_load_dword v15, v[22:23], off nt
	s_nop 0
	global_load_dword v16, v[24:25], off nt
	global_load_dword v17, v[26:27], off nt
	v_or_b32_e32 v22, 32, v2
	v_or_b32_e32 v24, 36, v2
	v_or_b32_e32 v26, 40, v2
	v_ashrrev_i32_e32 v23, 31, v22
	v_ashrrev_i32_e32 v25, 31, v24
	v_ashrrev_i32_e32 v27, 31, v26
	v_or_b32_e32 v28, 44, v2
	v_or_b32_e32 v30, 48, v2
	s_waitcnt lgkmcnt(0)
	v_or_b32_e32 v32, 52, v2
	v_or_b32_e32 v34, 56, v2
	v_or_b32_e32 v2, 60, v2
	v_lshlrev_b64 v[22:23], 12, v[22:23]
	v_lshlrev_b64 v[24:25], 12, v[24:25]
	v_lshlrev_b64 v[26:27], 12, v[26:27]
	v_ashrrev_i32_e32 v29, 31, v28
	v_ashrrev_i32_e32 v31, 31, v30
	v_ashrrev_i32_e32 v33, 31, v32
	v_ashrrev_i32_e32 v35, 31, v34
	v_ashrrev_i32_e32 v3, 31, v2
	v_lshl_add_u64 v[22:23], v[20:21], 0, v[22:23]
	v_lshl_add_u64 v[24:25], v[20:21], 0, v[24:25]
	v_lshl_add_u64 v[26:27], v[20:21], 0, v[26:27]
	v_lshlrev_b64 v[28:29], 12, v[28:29]
	v_lshlrev_b64 v[30:31], 12, v[30:31]
	v_lshlrev_b64 v[32:33], 12, v[32:33]
	v_lshlrev_b64 v[34:35], 12, v[34:35]
	v_lshlrev_b64 v[2:3], 12, v[2:3]
	v_lshl_add_u64 v[28:29], v[20:21], 0, v[28:29]
	v_lshl_add_u64 v[30:31], v[20:21], 0, v[30:31]
	v_lshl_add_u64 v[32:33], v[20:21], 0, v[32:33]
	v_lshl_add_u64 v[34:35], v[20:21], 0, v[34:35]
	v_lshl_add_u64 v[2:3], v[20:21], 0, v[2:3]
	global_load_dword v19, v[22:23], off nt
	global_load_dword v20, v[24:25], off nt
	global_load_dword v21, v[26:27], off nt
	s_nop 0
	global_load_dword v22, v[28:29], off nt
	global_load_dword v23, v[30:31], off nt
	global_load_dword v24, v[32:33], off nt
	global_load_dword v25, v[34:35], off nt
	global_load_dword v26, v[2:3], off nt
	v_bfe_u32 v7, v4, 3, 5
	v_lshlrev_b32_e32 v4, 3, v4
	v_and_b32_e32 v10, 56, v4
	v_mul_u32_u24_e32 v12, 0x41, v10
	v_lshlrev_b32_e32 v12, 2, v12
	v_lshlrev_b32_e32 v27, 2, v7
	v_lshlrev_b32_e32 v4, 1, v10
	v_mov_b32_e32 v5, v1
	v_add3_u32 v12, s33, v12, v27
	v_mul_u32_u24_e32 v27, 0x104, v6
	v_lshl_add_u64 v[2:3], s[20:21], 0, v[0:1]
	v_lshl_add_u64 v[4:5], s[0:1], 0, v[4:5]
	v_or_b32_e32 v10, 32, v7
	v_add3_u32 v0, s33, v27, v0
	v_readlane_b32 s6, v254, 61
	v_readlane_b32 s7, v254, 62
	v_readlane_b32 s8, v254, 63
	v_readlane_b32 s9, v255, 0
	v_readlane_b32 s10, v255, 1
	v_readlane_b32 s11, v255, 2
	v_readlane_b32 s12, v255, 3
	v_readlane_b32 s13, v255, 4
	v_readlane_b32 s14, v255, 5
	v_readlane_b32 s15, v255, 6
	v_readlane_b32 s16, v255, 7
	v_readlane_b32 s17, v255, 8
	v_readlane_b32 s18, v255, 9
	v_readlane_b32 s19, v255, 10
	s_branch .LBB0_1071
